# NA grid-row tile loop K/V staged by LDS-DMA into a 4-slot ring three tiles ahead, on top of the GQA+MLA wave-half ping-pong
# baseline (speedup 1.0000x reference)
.LBB0_160:
	s_andn2_b64 vcc, exec, s[4:5]
	s_cbranch_vccnz .LBB0_267
	s_cmp_eq_u32 s81, 0
	s_movk_i32 s2, 0x800
	s_cselect_b32 s69, s2, 0x840
	s_cmp_ge_i32 s72, s69
	s_cbranch_scc1 .LBB0_267
	v_ashrrev_i32_e32 v7, 1, v178
	s_movk_i32 s2, 0xffe0
	v_bfi_b32 v4, s2, v7, v178
	v_ashrrev_i32_e32 v5, 31, v4
	v_lshlrev_b32_e32 v3, 3, v178
	v_lshlrev_b64 v[110:111], 13, v[4:5]
	v_ashrrev_i32_e32 v114, 3, v178
	v_ashrrev_i32_e32 v118, 5, v178
	v_bfe_u32 v4, v3, 5, 1
	s_mov_b32 s2, 0x7ffffe
	v_and_or_b32 v4, v118, s2, v4
	v_lshlrev_b32_e32 v5, 5, v114
	v_and_b32_e32 v8, 24, v3
	s_movk_i32 s2, 0xe0
	v_and_or_b32 v5, v5, s2, v8
	s_add_u32 s89, s98, 0x4600000
	v_and_b32_e32 v116, 56, v3
	v_lshlrev_b32_e32 v4, 9, v4
	v_lshlrev_b32_e32 v5, 1, v5
	s_addc_u32 s26, s99, 0
	v_add3_u32 v113, 16, v4, v5
	v_lshlrev_b32_e32 v5, 1, v116
	v_lshlrev_b32_e32 v8, 4, v114
	s_movk_i32 s2, 0x70
	s_add_u32 s27, s98, 0x4600800
	v_lshlrev_b32_e32 v4, 7, v114
	v_bitop3_b32 v5, v5, v8, s2 bitop3:0x78
	s_addc_u32 s28, s99, 0
	v_add3_u32 v117, 16, v5, v4
	v_lshlrev_b32_e32 v4, 1, v178
	s_add_u32 s29, s98, 0x4601000
	v_bfe_u32 v6, v178, 5, 1
	v_and_b32_e32 v4, 32, v4
	s_movk_i32 s4, 0x118
	s_addc_u32 s36, s99, 0
	v_and_or_b32 v3, v3, s4, v4
	v_lshlrev_b32_e32 v4, 4, v178
	v_lshlrev_b32_e32 v119, 4, v6
	v_and_b32_e32 v0, 0x3fffffc0, v178
	v_and_b32_e32 v8, 0x70, v4
	v_bitop3_b32 v130, v119, v4, s2 bitop3:0x78
	s_movk_i32 s2, 0x60
	s_cmp_lg_u32 16, -1
	v_lshl_add_u32 v109, v0, 2, 16
	v_and_b32_e32 v0, 63, v178
	v_and_b32_e32 v2, 0xffffffe0, v7
	v_and_b32_e32 v5, 0xc0, v4
	v_bitop3_b32 v133, v119, v8, s2 bitop3:0x36
	s_cselect_b32 s2, 16, 0
	v_and_b32_e32 v108, 31, v178
	v_cmp_gt_u32_e64 s[76:77], 32, v0
	v_add3_u32 v135, v5, s2, v3
	v_ashrrev_i32_e32 v3, 31, v2
	v_and_b32_e32 v0, 32, v7
	v_writelane_b32 v254, s34, 18
	v_lshlrev_b64 v[120:121], 13, v[2:3]
	v_or_b32_e32 v2, v0, v108
	v_writelane_b32 v254, s35, 19
	s_lshl_b64 s[4:5], 1, s47
	v_cmp_ne_u32_e64 s[8:9], 31, v108
	v_med3_u32 v2, v2, 8, 56
	v_lshlrev_b32_e32 v5, 2, v6
	v_lshlrev_b32_e32 v112, 3, v6
	s_and_b32 s92, s4, 0xfff72ef6
	v_lshlrev_b32_e32 v122, 15, v6
	v_writelane_b32 v254, s8, 20
	v_add_u32_e32 v3, -8, v2
	v_add_u32_e32 v4, 8, v2
	v_subrev_u32_e32 v2, 24, v2
	v_or_b32_e32 v6, 32, v5
	s_cmp_lg_u64 s[92:93], 0
	v_writelane_b32 v254, s9, 21
	v_cmp_ge_u32_e32 vcc, v6, v3
	v_cmp_lt_i32_e64 s[8:9], v5, v2
	s_cselect_b64 s[6:7], -1, 0
	s_and_b64 s[8:9], vcc, s[8:9]
	v_writelane_b32 v254, s8, 22
	v_or_b32_e32 v6, 1, v5
	v_or_b32_e32 v7, 33, v5
	v_writelane_b32 v254, s9, 23
	v_cmp_lt_u32_e64 s[8:9], v6, v3
	v_cmp_ge_u32_e32 vcc, v7, v3
	v_cmp_lt_i32_e64 s[14:15], v6, v2
	v_writelane_b32 v254, s8, 24
	v_or_b32_e32 v6, 34, v5
	v_or_b32_e32 v7, 2, v5
	v_writelane_b32 v254, s9, 25
	v_cmp_lt_u32_e64 s[8:9], v5, v3
	v_cmp_lt_i32_e64 s[16:17], v7, v2
	v_bitop3_b32 v131, v119, v8, 32 bitop3:0x36
	v_writelane_b32 v254, s8, 26
	v_bitop3_b32 v132, v119, v8, 64 bitop3:0x36
	v_or_b32_e32 v8, 35, v5
	v_writelane_b32 v254, s9, 27
	s_and_b64 s[8:9], vcc, s[14:15]
	v_writelane_b32 v254, s8, 28
	v_cmp_ge_u32_e32 vcc, v6, v3
	v_or_b32_e32 v6, 3, v5
	v_writelane_b32 v254, s9, 29
	s_and_b64 s[8:9], vcc, s[16:17]
	v_writelane_b32 v254, s8, 30
	v_cmp_ge_u32_e32 vcc, v8, v3
	v_cmp_lt_i32_e64 s[22:23], v6, v2
	v_writelane_b32 v254, s9, 31
	v_cmp_lt_u32_e64 s[8:9], v6, v3
	v_or_b32_e32 v8, 40, v5
	v_or_b32_e32 v9, 8, v5
	v_writelane_b32 v254, s8, 32
	v_cmp_lt_i32_e64 s[24:25], v9, v2
	v_or_b32_e32 v10, 41, v5
	v_writelane_b32 v254, s9, 33
	v_cmp_lt_u32_e64 s[8:9], v7, v3
	v_or_b32_e32 v11, 10, v5
	v_cmp_lt_i32_e64 s[34:35], v11, v2
	v_writelane_b32 v254, s8, 34
	v_or_b32_e32 v12, 43, v5
	v_or_b32_e32 v13, 16, v5
	v_writelane_b32 v254, s9, 35
	s_and_b64 s[8:9], vcc, s[22:23]
	v_writelane_b32 v254, s8, 36
	v_cmp_ge_u32_e32 vcc, v8, v3
	v_or_b32_e32 v8, 9, v5
	v_writelane_b32 v254, s9, 37
	s_and_b64 s[8:9], vcc, s[24:25]
	v_writelane_b32 v254, s8, 38
	v_cmp_ge_u32_e32 vcc, v10, v3
	v_cmp_lt_i32_e64 s[30:31], v8, v2
	v_writelane_b32 v254, s9, 39
	v_cmp_lt_u32_e64 s[8:9], v8, v3
	v_or_b32_e32 v10, 42, v5
	v_cmp_lt_u32_e64 s[42:43], v13, v4
	v_writelane_b32 v254, s8, 40
	v_or_b32_e32 v15, 18, v5
	v_or_b32_e32 v14, 19, v5
	v_writelane_b32 v254, s9, 41
	v_cmp_lt_u32_e64 s[8:9], v9, v3
	v_cmp_lt_u32_e64 s[50:51], v15, v4
	v_cmp_lt_u32_e64 s[52:53], v14, v4
	v_writelane_b32 v254, s8, 42
	v_or_b32_e32 v17, 24, v5
	v_or_b32_e32 v16, 25, v5
	v_writelane_b32 v254, s9, 43
	s_and_b64 s[8:9], vcc, s[30:31]
	v_writelane_b32 v254, s8, 44
	v_cmp_ge_u32_e32 vcc, v10, v3
	v_or_b32_e32 v10, 11, v5
	v_writelane_b32 v254, s9, 45
	s_and_b64 s[8:9], vcc, s[34:35]
	v_writelane_b32 v254, s8, 46
	v_cmp_ge_u32_e32 vcc, v12, v3
	v_cmp_lt_i32_e64 s[40:41], v10, v2
	v_writelane_b32 v254, s9, 47
	v_cmp_lt_u32_e64 s[8:9], v10, v3
	v_or_b32_e32 v12, 17, v5
	v_cmp_lt_u32_e64 s[44:45], v12, v4
	v_writelane_b32 v254, s8, 48
	v_cmp_lt_u32_e64 s[58:59], v17, v4
	v_cmp_lt_u32_e64 s[60:61], v16, v4
	v_writelane_b32 v254, s9, 49
	v_cmp_lt_u32_e64 s[8:9], v11, v3
	v_or_b32_e32 v18, 26, v5
	v_cmp_lt_u32_e64 s[66:67], v18, v4
	v_writelane_b32 v254, s8, 50
	v_cmp_lt_i32_e64 s[22:23], v18, v2
	v_cmp_lt_i32_e64 s[10:11], v12, v2
	v_writelane_b32 v254, s9, 51
	s_and_b64 s[8:9], vcc, s[40:41]
	v_writelane_b32 v254, s8, 52
	v_cmp_ge_u32_e32 vcc, v13, v3
	v_cmp_lt_i32_e64 s[12:13], v13, v2
	v_writelane_b32 v254, s9, 53
	s_and_b64 s[8:9], vcc, s[42:43]
	v_cmp_ge_u32_e32 vcc, v12, v3
	s_and_b64 s[44:45], vcc, s[44:45]
	v_cmp_ge_u32_e32 vcc, v15, v3
	s_and_b64 s[50:51], vcc, s[50:51]
	v_cmp_ge_u32_e32 vcc, v14, v3
	s_and_b64 s[52:53], vcc, s[52:53]
	v_cmp_ge_u32_e32 vcc, v17, v3
	s_and_b64 s[58:59], vcc, s[58:59]
	v_cmp_ge_u32_e32 vcc, v16, v3
	s_and_b64 s[60:61], vcc, s[60:61]
	v_cmp_ge_u32_e32 vcc, v18, v3
	v_or_b32_e32 v18, 27, v5
	v_cmp_lt_i32_e64 s[14:15], v14, v2
	v_cmp_lt_i32_e64 s[16:17], v15, v2
	v_cmp_lt_i32_e64 s[18:19], v16, v2
	v_cmp_lt_i32_e64 s[20:21], v17, v2
	v_cmp_lt_i32_e64 s[30:31], v18, v2
	v_sub_u32_e32 v2, v5, v108
	v_sub_u32_e32 v2, v2, v0
	s_and_b64 s[66:67], vcc, s[66:67]
	v_cmp_ge_u32_e32 vcc, v18, v3
	v_add_u32_e32 v3, 59, v2
	v_min_i32_e32 v3, 15, v3
	v_lshlrev_b32_e32 v140, 2, v3
	v_and_b32_e32 v3, 0xffffff80, v178
	v_sub_u32_e32 v141, 16, v3
	v_add_u32_e32 v3, 27, v2
	v_med3_i32 v3, v3, -15, 15
	v_lshlrev_b32_e32 v142, 2, v3
	v_add_u32_e32 v3, 58, v2
	v_min_i32_e32 v3, 15, v3
	v_lshlrev_b32_e32 v143, 2, v3
	v_add_u32_e32 v3, 26, v2
	v_med3_i32 v3, v3, -15, 15
	v_lshlrev_b32_e32 v144, 2, v3
	v_add_u32_e32 v3, 57, v2
	v_min_i32_e32 v3, 15, v3
	v_lshlrev_b32_e32 v145, 2, v3
	v_sub_u32_e32 v3, v16, v108
	v_sub_u32_e32 v3, v3, v0
	v_med3_i32 v3, v3, -15, 15
	v_lshlrev_b32_e32 v146, 2, v3
	v_add_u32_e32 v3, 56, v2
	v_min_i32_e32 v3, 15, v3
	v_lshlrev_b32_e32 v147, 2, v3
	v_sub_u32_e32 v3, v17, v108
	v_sub_u32_e32 v3, v3, v0
	v_med3_i32 v3, v3, -15, 15
	v_lshlrev_b32_e32 v148, 2, v3
	v_add_u32_e32 v3, 51, v2
	v_min_i32_e32 v3, 15, v3
	v_lshlrev_b32_e32 v149, 2, v3
	v_sub_u32_e32 v3, v14, v108
	v_sub_u32_e32 v3, v3, v0
	v_med3_i32 v3, v3, -15, 15
	v_lshlrev_b32_e32 v150, 2, v3
	v_add_u32_e32 v3, 50, v2
	v_min_i32_e32 v3, 15, v3
	v_lshlrev_b32_e32 v151, 2, v3
	v_sub_u32_e32 v3, v15, v108
	v_sub_u32_e32 v3, v3, v0
	v_med3_i32 v3, v3, -15, 15
	v_lshlrev_b32_e32 v152, 2, v3
	v_add_u32_e32 v3, 49, v2
	v_min_i32_e32 v3, 15, v3
	v_lshlrev_b32_e32 v153, 2, v3
	v_sub_u32_e32 v3, v12, v108
	v_sub_u32_e32 v3, v3, v0
	v_med3_i32 v3, v3, -15, 15
	v_lshlrev_b32_e32 v154, 2, v3
	v_add_u32_e32 v3, 48, v2
	v_min_i32_e32 v3, 15, v3
	v_lshlrev_b32_e32 v155, 2, v3
	v_sub_u32_e32 v3, v13, v108
	v_sub_u32_e32 v3, v3, v0
	v_med3_i32 v3, v3, -15, 15
	v_lshlrev_b32_e32 v156, 2, v3
	v_add_u32_e32 v3, 43, v2
	v_med3_i32 v3, v3, -15, 15
	v_lshlrev_b32_e32 v157, 2, v3
	v_sub_u32_e32 v3, v10, v108
	v_sub_u32_e32 v3, v3, v0
	v_max_i32_e32 v3, -15, v3
	v_lshlrev_b32_e32 v158, 2, v3
	v_add_u32_e32 v3, 42, v2
	v_med3_i32 v3, v3, -15, 15
	v_lshlrev_b32_e32 v159, 2, v3
	v_sub_u32_e32 v3, v11, v108
	v_sub_u32_e32 v3, v3, v0
	v_max_i32_e32 v3, -15, v3
	v_lshlrev_b32_e32 v160, 2, v3
	v_add_u32_e32 v3, 41, v2
	v_med3_i32 v3, v3, -15, 15
	v_lshlrev_b32_e32 v161, 2, v3
	v_sub_u32_e32 v3, v8, v108
	v_sub_u32_e32 v3, v3, v0
	v_max_i32_e32 v3, -15, v3
	v_lshlrev_b32_e32 v162, 2, v3
	v_add_u32_e32 v3, 40, v2
	v_med3_i32 v3, v3, -15, 15
	v_lshlrev_b32_e32 v163, 2, v3
	v_sub_u32_e32 v3, v9, v108
	v_sub_u32_e32 v3, v3, v0
	v_max_i32_e32 v3, -15, v3
	v_lshlrev_b32_e32 v164, 2, v3
	v_add_u32_e32 v3, 35, v2
	v_med3_i32 v3, v3, -15, 15
	v_lshlrev_b32_e32 v165, 2, v3
	v_sub_u32_e32 v3, v6, v108
	v_sub_u32_e32 v3, v3, v0
	v_max_i32_e32 v3, -15, v3
	v_lshlrev_b32_e32 v166, 2, v3
	v_add_u32_e32 v3, 34, v2
	v_med3_i32 v3, v3, -15, 15
	v_lshlrev_b32_e32 v167, 2, v3
	v_sub_u32_e32 v3, v7, v108
	v_sub_u32_e32 v0, v3, v0
	v_max_i32_e32 v0, -15, v0
	v_lshlrev_b32_e32 v168, 2, v0
	v_add_u32_e32 v0, 33, v2
	v_med3_i32 v0, v0, -15, 15
	v_lshlrev_b32_e32 v169, 2, v0
	v_add_u32_e32 v0, 1, v2
	v_max_i32_e32 v0, -15, v0
	v_lshlrev_b32_e32 v170, 2, v0
	v_add_u32_e32 v0, 32, v2
	v_writelane_b32 v254, s8, 54
	v_med3_i32 v0, v0, -15, 15
	s_movk_i32 s2, 0x1e0
	v_writelane_b32 v254, s9, 55
	v_cmp_lt_u32_e64 s[70:71], v18, v4
	v_lshlrev_b32_e32 v171, 2, v0
	v_max_i32_e32 v0, -15, v2
	v_ashrrev_i32_e32 v115, 31, v114
	v_lshl_add_u32 v134, v108, 2, v109
	v_lshl_add_u32 v136, v108, 7, 16
	v_ashrrev_i32_e32 v179, 31, v178
	v_mov_b32_e32 v123, v1
	v_cmp_gt_i32_e64 s[4:5], s2, v178
	v_lshl_add_u32 v137, v178, 2, 16
	v_ashrrev_i32_e32 v138, 7, v178
	s_mov_b32 s43, 0x14000
	s_movk_i32 s42, 0x2000
	s_and_b64 s[70:71], vcc, s[70:71]
	v_add_u32_e32 v139, 0x2000, v135
	v_lshlrev_b32_e32 v172, 2, v0
	v_readlane_b32 s37, v254, 7
	s_mov_b32 s2, s72
	v_and_b32_e32 v2, 63, v178
	v_lshrrev_b32_e32 v3, 6, v178
	v_lshrrev_b32_e32 v4, 3, v2
	s_nop 0
	v_readfirstlane_b32 s32, v3
	v_lshlrev_b32_e32 v3, 16, v3
	v_and_b32_e32 v5, 7, v2
	v_xor_b32_e32 v5, v5, v4
	v_lshlrev_b32_e32 v5, 4, v5
	v_lshl_add_u32 v5, v4, 13, v5
	v_add_u32_e32 v220, v3, v5
	v_and_b32_e32 v4, 31, v2
	v_lshrrev_b32_e32 v4, 2, v4
	v_lshrrev_b32_e32 v5, 5, v2
	v_lshlrev_b32_e32 v5, 6, v5
	v_lshl_add_u32 v5, v4, 13, v5
	v_and_b32_e32 v4, 3, v2
	v_lshl_add_u32 v5, v4, 4, v5
	v_add_u32_e32 v221, v3, v5
	v_add_u32_e32 v221, 0x800, v221
	s_lshl_b32 s32, s32, 10
	s_add_i32 s32, s32, 16
	s_nop 0
	s_nop 0
	s_nop 0
	s_nop 0
	s_nop 0
	s_nop 0
	s_nop 0
	s_nop 0
	s_nop 0
	s_nop 0
	s_nop 0
	s_nop 0
	s_nop 0
	s_nop 0
	s_nop 0
	s_nop 0
	s_nop 0
	s_nop 0
	s_nop 0
	s_nop 0
	s_nop 0
	s_nop 0
	s_nop 0
	s_nop 0
	s_nop 0
	s_nop 0
	s_nop 0
	s_nop 0
	s_nop 0
	s_nop 0
	s_nop 0
	s_nop 0
	s_branch .LBB0_165
